# phase-0 prenorm row loop software-pipelined: gain vectors kept in registers, next row prefetched before this row's stores
# baseline (speedup 1.0000x reference)
; __device__ __forceinline__ unsigned cvtpk(float lo, float hi) { typedef __bf16 bf2 __attribute__((ext_vector_type(2))); f32x2 v = {lo, hi}; bf2 b = __builtin_convertvector(v, bf2); return __builtin_bit_cast(unsigned, b); }
; __device__ __forceinline__ void prenorm_rows(const float* x, const float* g, bf16_t* xn, int gw, int NGW, int lane) {
;     for (int row = gw; row < NTOK; row += NGW) {
;         const f32x4* xr = (const f32x4*)(x + (size_t)row * DMODEL) + lane; f32x4 v[4]; float ss = 0.f;
; #pragma unroll
;         for (int j = 0; j < 4; ++j) { v[j] = __builtin_nontemporal_load(xr + 64 * j); ss += (v[j][0] * v[j][0] + v[j][1] * v[j][1]) + (v[j][2] * v[j][2] + v[j][3] * v[j][3]); }
;         const float rs = __builtin_amdgcn_rsqf(wave_sum(ss) * (1.f / DMODEL) + EPSN);
;         u32x2* o = (u32x2*)(xn + (size_t)row * DMODEL) + lane;
; #pragma unroll
;         for (int j = 0; j < 4; ++j) { const f32x4 gg = ((const f32x4*)g)[lane + 64 * j]; u32x2 w; w.x = cvtpk(v[j][0] * rs * gg[0], v[j][1] * rs * gg[1]); w.y = cvtpk(v[j][2] * rs * gg[2], v[j][3] * rs * gg[3]); o[64 * j] = w; }
;     }
.LBB0_65:
	s_or_b64 exec, exec, s[8:9]
	s_cmpk_gt_i32 s3, 0x3fff
	s_cbranch_scc1 .LBB0_68
	v_mbcnt_lo_u32_b32 v2, -1, 0
	v_mbcnt_hi_u32_b32 v2, -1, v2
	v_and_b32_e32 v3, 64, v2
	v_add_u32_e32 v3, 64, v3
	v_xor_b32_e32 v4, 1, v2
	v_cmp_lt_i32_e32 vcc, v4, v3
	s_load_dwordx4 s[8:11], s[6:7], 0x0
	v_lshlrev_b32_e32 v6, 4, v38
	v_cndmask_b32_e32 v4, v2, v4, vcc
	v_lshlrev_b32_e32 v10, 2, v4
	v_xor_b32_e32 v4, 2, v2
	v_cmp_lt_i32_e32 vcc, v4, v3
	v_mov_b32_e32 v7, 0
	s_ashr_i32 s6, s27, 31
	v_cndmask_b32_e32 v4, v2, v4, vcc
	v_lshlrev_b32_e32 v11, 2, v4
	v_xor_b32_e32 v4, 4, v2
	v_cmp_lt_i32_e32 vcc, v4, v3
	s_ashr_i32 s7, s36, 31
	v_mov_b32_e32 v9, v7
	v_cndmask_b32_e32 v4, v2, v4, vcc
	v_lshlrev_b32_e32 v12, 2, v4
	v_xor_b32_e32 v4, 8, v2
	v_cmp_lt_i32_e32 vcc, v4, v3
	s_nop 1
	v_cndmask_b32_e32 v4, v2, v4, vcc
	v_lshlrev_b32_e32 v13, 2, v4
	v_xor_b32_e32 v4, 16, v2
	v_cmp_lt_i32_e32 vcc, v4, v3
	s_nop 1
	v_cndmask_b32_e32 v4, v2, v4, vcc
	v_lshlrev_b32_e32 v14, 2, v4
	v_xor_b32_e32 v4, 32, v2
	v_cmp_lt_i32_e32 vcc, v4, v3
	s_nop 1
	v_cndmask_b32_e32 v2, v2, v4, vcc
	v_lshlrev_b32_e32 v15, 2, v2
	s_waitcnt lgkmcnt(0)
	v_lshl_add_u64 v[2:3], s[10:11], 0, v[6:7]
	s_add_u32 s10, s27, s36
	s_addc_u32 s11, s6, s7
	s_lshl_b64 s[6:7], s[10:11], 12
	s_add_u32 s6, s8, s6
	s_addc_u32 s7, s9, s7
	v_lshl_add_u64 v[4:5], s[6:7], 0, v[6:7]
	s_mov_b64 s[6:7], 0xc00
	s_ashr_i32 s27, s26, 31
	v_lshl_add_u64 v[4:5], v[4:5], 0, s[6:7]
	s_lshl_b64 s[6:7], s[26:27], 12
	s_lshl_b64 s[8:9], s[10:11], 11
	s_add_u32 s4, s4, s8
	s_addc_u32 s5, s5, s9
	v_lshl_add_u64 v[6:7], s[4:5], 0, v[8:9]
	s_mov_b64 s[4:5], 0x9d00400
	v_lshl_add_u64 v[6:7], v[6:7], 0, s[4:5]
	s_lshl_b64 s[4:5], s[26:27], 11
	v_mov_b32_e32 v8, 0x358637bd
	global_load_dwordx4 v[76:79], v[2:3], off
	global_load_dwordx4 v[80:83], v[2:3], off offset:1024
	global_load_dwordx4 v[84:87], v[2:3], off offset:2048
	global_load_dwordx4 v[88:91], v[2:3], off offset:3072
	global_load_dwordx4 v[60:63], v[4:5], off offset:-3072 nt
	global_load_dwordx4 v[64:67], v[4:5], off offset:-2048 nt
	global_load_dwordx4 v[68:71], v[4:5], off offset:-1024 nt
	global_load_dwordx4 v[72:75], v[4:5], off nt
	s_waitcnt vmcnt(0)
.LBB0_67:
	v_mov_b64_e32 v[16:17], v[60:61]
	v_mov_b64_e32 v[18:19], v[62:63]
	v_mov_b64_e32 v[20:21], v[64:65]
	v_mov_b64_e32 v[22:23], v[66:67]
	v_mov_b64_e32 v[24:25], v[68:69]
	v_mov_b64_e32 v[26:27], v[70:71]
	v_mov_b64_e32 v[28:29], v[72:73]
	v_mov_b64_e32 v[30:31], v[74:75]
	s_add_i32 s3, s3, s26
	v_lshl_add_u64 v[4:5], v[4:5], 0, s[6:7]
	s_cmpk_gt_i32 s3, 0x3fff
	s_cbranch_scc1 .Lpn_nopf
	global_load_dwordx4 v[60:63], v[4:5], off offset:-3072 nt
	global_load_dwordx4 v[64:67], v[4:5], off offset:-2048 nt
	global_load_dwordx4 v[68:71], v[4:5], off offset:-1024 nt
	global_load_dwordx4 v[72:75], v[4:5], off nt
.Lpn_nopf:
	v_pk_mul_f32 v[36:37], v[18:19], v[18:19]
	v_pk_mul_f32 v[38:39], v[16:17], v[16:17]
	v_pk_mul_f32 v[40:41], v[22:23], v[22:23]
	v_pk_mul_f32 v[42:43], v[20:21], v[20:21]
	v_pk_mov_b32 v[48:49], v[38:39], v[36:37] op_sel:[1,0]
	v_mov_b32_e32 v39, v37
	v_pk_mov_b32 v[36:37], v[42:43], v[40:41] op_sel:[1,0]
	v_mov_b32_e32 v43, v41
	v_mul_f32_e32 v47, v29, v29
	v_mul_f32_e32 v44, v25, v25
	v_mul_f32_e32 v46, v27, v27
	v_pk_add_f32 v[38:39], v[48:49], v[38:39]
	v_pk_add_f32 v[36:37], v[36:37], v[42:43]
	v_mul_f32_e32 v9, v28, v28
	v_mul_f32_e32 v50, v30, v30
	v_mul_f32_e32 v51, v31, v31
	v_pk_fma_f32 v[40:41], v[24:25], v[24:25], v[44:45] op_sel_hi:[1,1,0]
	v_pk_fma_f32 v[44:45], v[26:27], v[26:27], v[46:47] op_sel_hi:[1,1,0]
	v_pk_add_f32 v[38:39], v[38:39], v[38:39] op_sel:[0,1] op_sel_hi:[1,0]
	v_pk_add_f32 v[36:37], v[36:37], v[36:37] op_sel:[0,1] op_sel_hi:[1,0]
	v_mov_b32_e32 v41, v50
	v_mov_b32_e32 v45, v51
	v_mov_b32_e32 v39, v9
	v_mov_b32_e32 v37, v47
	v_pk_add_f32 v[40:41], v[40:41], v[44:45]
	v_pk_add_f32 v[36:37], v[38:39], v[36:37]
	s_nop 0
	v_pk_add_f32 v[36:37], v[36:37], v[40:41]
	s_nop 0
	v_add_f32_e32 v9, v36, v37
	ds_bpermute_b32 v36, v10, v9
	s_waitcnt lgkmcnt(0)
	v_add_f32_e32 v9, v9, v36
	ds_bpermute_b32 v36, v11, v9
	s_waitcnt lgkmcnt(0)
	v_add_f32_e32 v9, v9, v36
	ds_bpermute_b32 v36, v12, v9
	s_waitcnt lgkmcnt(0)
	v_add_f32_e32 v9, v9, v36
	ds_bpermute_b32 v36, v13, v9
	s_waitcnt lgkmcnt(0)
	v_add_f32_e32 v9, v9, v36
	ds_bpermute_b32 v36, v14, v9
	s_waitcnt lgkmcnt(0)
	v_add_f32_e32 v9, v9, v36
	ds_bpermute_b32 v36, v15, v9
	s_waitcnt lgkmcnt(0)
	v_add_f32_e32 v9, v9, v36
	v_fmamk_f32 v9, v9, 0x3a800000, v8
	v_rsq_f32_e32 v36, v9
	s_nop 0
	v_pk_mul_f32 v[16:17], v[16:17], v[36:37] op_sel_hi:[1,0]
	v_pk_mul_f32 v[18:19], v[18:19], v[36:37] op_sel_hi:[1,0]
	v_pk_mul_f32 v[16:17], v[76:77], v[16:17]
	v_pk_mul_f32 v[18:19], v[78:79], v[18:19]
	v_cvt_pk_bf16_f32 v16, v16, v17
	v_cvt_pk_bf16_f32 v17, v18, v19
	global_store_dwordx2 v[6:7], v[16:17], off offset:-1024
	v_pk_mul_f32 v[20:21], v[20:21], v[36:37] op_sel_hi:[1,0]
	v_pk_mul_f32 v[22:23], v[22:23], v[36:37] op_sel_hi:[1,0]
	v_pk_mul_f32 v[16:17], v[80:81], v[20:21]
	v_pk_mul_f32 v[18:19], v[82:83], v[22:23]
	v_cvt_pk_bf16_f32 v16, v16, v17
	v_cvt_pk_bf16_f32 v17, v18, v19
	global_store_dwordx2 v[6:7], v[16:17], off offset:-512
	v_pk_mul_f32 v[20:21], v[24:25], v[36:37] op_sel_hi:[1,0]
	v_pk_mul_f32 v[22:23], v[26:27], v[36:37] op_sel_hi:[1,0]
	v_pk_mul_f32 v[16:17], v[84:85], v[20:21]
	v_pk_mul_f32 v[18:19], v[86:87], v[22:23]
	v_cvt_pk_bf16_f32 v16, v16, v17
	v_cvt_pk_bf16_f32 v17, v18, v19
	global_store_dwordx2 v[6:7], v[16:17], off
	v_pk_mul_f32 v[20:21], v[28:29], v[36:37] op_sel_hi:[1,0]
	v_pk_mul_f32 v[22:23], v[30:31], v[36:37] op_sel_hi:[1,0]
	v_pk_mul_f32 v[16:17], v[88:89], v[20:21]
	v_pk_mul_f32 v[18:19], v[90:91], v[22:23]
	v_cvt_pk_bf16_f32 v16, v16, v17
	v_cvt_pk_bf16_f32 v17, v18, v19
	global_store_dwordx2 v[6:7], v[16:17], off offset:512
	v_lshl_add_u64 v[6:7], v[6:7], 0, s[4:5]
	s_waitcnt vmcnt(4)
	s_cbranch_scc0 .LBB0_67
